# E1_sw0x2
# baseline (speedup 1.0000x reference)
_Z11mega_kernel6Paramsiii:
	s_load_dwordx4 s[56:59], s[0:1], 0xd8
	s_mov_b64 s[74:75], s[0:1]
	s_mov_b32 s72, s2
	s_mov_b32 s2, 0
	v_writelane_b32 v226, s2, 2
	s_waitcnt lgkmcnt(0)
	s_cmp_lg_u32 s58, 0
	s_cselect_b64 s[0:1], -1, 0
	v_writelane_b32 v227, s0, 0
	s_cmp_eq_u32 s58, 0
	s_nop 0
	v_writelane_b32 v227, s1, 1
	s_cbranch_scc1 .LBB0_16
	s_load_dwordx2 s[6:7], s[74:75], 0xd0
	v_and_b32_e32 v1, 0x3ff, v0
	v_cmp_eq_u32_e32 vcc, 0, v1
	s_waitcnt lgkmcnt(0)
	s_add_u32 s0, s6, 0xf000000
	s_addc_u32 s1, s7, 0
	s_and_saveexec_b64 s[4:5], vcc
	s_cbranch_execz .LBB0_22
	s_getreg_b32 s2, hwreg(HW_REG_XCC_ID, 0, 4)
	s_mov_b64 s[10:11], exec
	s_and_b32 s2, s2, 15
	s_lshl_b32 s3, s2, 8
	v_mbcnt_lo_u32_b32 v1, s10, 0
	s_add_u32 s8, s0, s3
	v_mbcnt_hi_u32_b32 v1, s11, v1
	s_addc_u32 s9, s1, 0
	v_cmp_eq_u32_e32 vcc, 0, v1
	s_and_saveexec_b64 s[12:13], vcc
	s_cbranch_execz .LBB0_4
	s_bcnt1_i32_b64 s3, s[10:11]
	v_mov_b32_e32 v1, 0
	v_mov_b32_e32 v2, s3
	global_atomic_add v1, v2, s[8:9] offset:1024

.LBB0_725:
	v_readlane_b32 s22, v227, 49
	v_readlane_b32 s0, v226, 2
	s_cmp_eq_u32 s22, 1
	s_cselect_b32 s1, 1, 0
	s_cmp_lt_u32 s0, 2
	s_cselect_b32 s1, s1, 0
	s_add_i32 s0, s0, s1
	s_sub_i32 s22, s22, s1
	v_writelane_b32 v226, s0, 2
	s_add_i32 s22, s22, 1
	s_cmp_ge_i32 s22, s57
	s_cselect_b64 s[0:1], -1, 0
	s_cmp_lt_i32 s22, s57
	v_readlane_b32 s8, v227, 0
	s_cselect_b64 s[6:7], -1, 0
	v_readlane_b32 s9, v227, 1
	s_and_b64 s[6:7], s[8:9], s[6:7]
	s_andn2_b64 vcc, exec, s[6:7]
	v_readlane_b32 s23, v227, 50
	s_cbranch_vccnz .LBB0_27
	v_readlane_b32 s8, v227, 17
	v_readlane_b32 s9, v227, 18
	s_mov_b64 s[6:7], -1
	s_and_b64 vcc, exec, s[8:9]
	s_cbranch_vccz .LBB0_765
	s_waitcnt vmcnt(0)
	s_waitcnt vmcnt(0) lgkmcnt(0)
	s_barrier
	s_mov_b64 s[6:7], exec
	v_readlane_b32 s8, v227, 19
	v_readlane_b32 s9, v227, 20
	s_and_b64 s[8:9], s[6:7], s[8:9]
	s_mov_b64 exec, s[8:9]
	s_cbranch_execz .LBB0_764
	s_mov_b64 s[8:9], exec
	v_mbcnt_lo_u32_b32 v0, s8, 0
	v_mbcnt_hi_u32_b32 v0, s9, v0
	v_cmp_eq_u32_e32 vcc, 0, v0
	s_waitcnt vmcnt(0) expcnt(0) lgkmcnt(0)
	s_and_saveexec_b64 s[10:11], vcc
	s_cbranch_execz .LBB0_730
	s_bcnt1_i32_b64 s2, s[8:9]
	v_readlane_b32 s8, v227, 21
	v_mov_b32_e32 v2, s2
	v_readlane_b32 s9, v227, 22
	s_nop 4
	global_atomic_add v2, v1, v2, s[8:9] sc0
